# PLE projection scratch (phase 9 -> 10, same lanes) stored lane-linear: 1 KiB contiguous per wave store/load instead of 16 row segments
# speedup vs baseline: 1.0374x; 1.0003x over previous
; __device__ __forceinline__ unsigned cvt_pk_bf16(float lo, float hi) { const f32x2 v = {lo, hi}; return __builtin_bit_cast(unsigned, __builtin_convertvector(v, bfx2_t)); }
;     __device__ __forceinline__ void operator()(const AccT& acc, const Unit& u, int ui, int wr, int wc, int fr, int fq) const {
; #pragma unroll
;         for (int ai = 0; ai < 2; ++ai)
; #pragma unroll
;             for (int m = 0; m < 4; ++m) {
;                 const int row = u.pm * 256 + ai * 128 + wr * 64 + m * 16 + fr;
;                 bf16_t* p = O + (size_t)row * DM + u.pn * 256 + wc * 32 + 8 * fq;
; #pragma unroll
;                 for (int bj = 0; bj < 2; ++bj) {
;                     const f32x4 a0 = acc[ai][bj][m][0], a1 = acc[ai][bj][m][1];
;                     u32x4 w; w.x = cvt_pk_bf16(a0[0], a0[1]); w.y = cvt_pk_bf16(a0[2], a0[3]); w.z = cvt_pk_bf16(a1[0], a1[1]); w.w = cvt_pk_bf16(a1[2], a1[3]);
;                     *GP(u32x4, p + bj * 128) = w;
;                 }
.LBB0_154:
	s_lshl_b32 s26, s72, 2
	s_add_i32 s26, s26, s76
	s_lshl_b32 s26, s26, 17
	s_mov_b32 s27, 0
	v_and_b32_e32 v174, 0xffffffc0, v162
	v_lshlrev_b32_e32 v174, 8, v174
	v_lshl_add_u32 v174, v208, 4, v174
	v_mov_b32_e32 v175, 0
	v_lshl_add_u64 v[174:175], s[26:27], 0, v[174:175]
	v_lshl_add_u32 v136, s72, 8, v132
	v_cvt_pk_bf16_f32 v116, v116, v117
	v_cvt_pk_bf16_f32 v117, v118, v119
	v_cvt_pk_bf16_f32 v118, v112, v113
	v_or_b32_e32 v112, 16, v136
	v_cvt_pk_bf16_f32 v100, v100, v101
	v_cvt_pk_bf16_f32 v101, v102, v103
	v_cvt_pk_bf16_f32 v102, v96, v97
	v_or_b32_e32 v96, 32, v136
	v_cvt_pk_bf16_f32 v84, v84, v85
	v_cvt_pk_bf16_f32 v85, v86, v87
	v_cvt_pk_bf16_f32 v86, v80, v81
	v_or_b32_e32 v80, 48, v136
	v_cvt_pk_bf16_f32 v68, v68, v69
	v_cvt_pk_bf16_f32 v69, v70, v71
	v_cvt_pk_bf16_f32 v70, v64, v65
	v_add_u32_e32 v64, 0x80, v136
	v_cvt_pk_bf16_f32 v52, v52, v53
	v_cvt_pk_bf16_f32 v53, v54, v55
	v_cvt_pk_bf16_f32 v54, v48, v49
	v_add_u32_e32 v48, 0x90, v136
	v_cvt_pk_bf16_f32 v36, v36, v37
	v_cvt_pk_bf16_f32 v37, v38, v39
	v_cvt_pk_bf16_f32 v38, v32, v33
	v_add_u32_e32 v32, 0xa0, v136
	v_cvt_pk_bf16_f32 v20, v20, v21
	v_cvt_pk_bf16_f32 v21, v22, v23
	v_cvt_pk_bf16_f32 v22, v16, v17
	v_add_u32_e32 v16, 0xb0, v136
	s_lshl_b32 s12, s76, 8
	v_ashrrev_i32_e32 v137, 31, v136
	v_ashrrev_i32_e32 v113, 31, v112
	v_ashrrev_i32_e32 v97, 31, v96
	v_ashrrev_i32_e32 v81, 31, v80
	v_ashrrev_i32_e32 v65, 31, v64
	v_ashrrev_i32_e32 v49, 31, v48
	v_ashrrev_i32_e32 v33, 31, v32
	v_ashrrev_i32_e32 v17, 31, v16
	s_ashr_i32 s13, s12, 31
	v_lshlrev_b64 v[138:139], 11, v[136:137]
	v_lshlrev_b64 v[112:113], 11, v[112:113]
	v_lshlrev_b64 v[96:97], 11, v[96:97]
	v_lshlrev_b64 v[80:81], 11, v[80:81]
	v_lshlrev_b64 v[64:65], 11, v[64:65]
	v_lshlrev_b64 v[48:49], 11, v[48:49]
	v_lshlrev_b64 v[32:33], 11, v[32:33]
	v_lshlrev_b64 v[16:17], 11, v[16:17]
	v_lshl_add_u64 v[138:139], s[16:17], 0, v[138:139]
	s_lshl_b64 s[12:13], s[12:13], 1
	v_lshl_add_u64 v[112:113], s[16:17], 0, v[112:113]
	v_lshl_add_u64 v[96:97], s[16:17], 0, v[96:97]
	v_lshl_add_u64 v[80:81], s[16:17], 0, v[80:81]
	v_lshl_add_u64 v[64:65], s[16:17], 0, v[64:65]
	v_lshl_add_u64 v[48:49], s[16:17], 0, v[48:49]
	v_lshl_add_u64 v[32:33], s[16:17], 0, v[32:33]
	v_lshl_add_u64 v[16:17], s[16:17], 0, v[16:17]
	v_lshl_add_u64 v[138:139], v[138:139], 0, s[12:13]
	v_lshl_add_u64 v[112:113], v[112:113], 0, s[12:13]
	v_lshl_add_u64 v[96:97], v[96:97], 0, s[12:13]
	v_lshl_add_u64 v[80:81], v[80:81], 0, s[12:13]
	v_lshl_add_u64 v[64:65], v[64:65], 0, s[12:13]
	v_lshl_add_u64 v[48:49], v[48:49], 0, s[12:13]
	v_lshl_add_u64 v[32:33], v[32:33], 0, s[12:13]
	v_lshl_add_u64 v[16:17], v[16:17], 0, s[12:13]
	v_lshl_add_u64 v[138:139], v[138:139], 0, s[62:63]
	v_lshl_add_u64 v[112:113], v[112:113], 0, s[62:63]
	v_lshl_add_u64 v[96:97], v[96:97], 0, s[62:63]
	v_lshl_add_u64 v[80:81], v[80:81], 0, s[62:63]
	v_lshl_add_u64 v[64:65], v[64:65], 0, s[62:63]
	v_lshl_add_u64 v[48:49], v[48:49], 0, s[62:63]
	v_lshl_add_u64 v[32:33], v[32:33], 0, s[62:63]
	v_lshl_add_u64 v[16:17], v[16:17], 0, s[62:63]
	v_lshl_add_u64 v[138:139], v[138:139], 0, v[168:169]
	v_cvt_pk_bf16_f32 v120, v120, v121
	v_cvt_pk_bf16_f32 v121, v122, v123
	v_cvt_pk_bf16_f32 v122, v124, v125
	v_cvt_pk_bf16_f32 v123, v126, v127
	v_cvt_pk_bf16_f32 v119, v114, v115
	v_lshl_add_u64 v[112:113], v[112:113], 0, v[168:169]
	v_cvt_pk_bf16_f32 v108, v108, v109
	v_cvt_pk_bf16_f32 v109, v110, v111
	v_cvt_pk_bf16_f32 v110, v104, v105
	v_cvt_pk_bf16_f32 v111, v106, v107
	v_cvt_pk_bf16_f32 v103, v98, v99
	v_lshl_add_u64 v[96:97], v[96:97], 0, v[168:169]
	v_cvt_pk_bf16_f32 v92, v92, v93
	v_cvt_pk_bf16_f32 v93, v94, v95
	v_cvt_pk_bf16_f32 v94, v88, v89
	v_cvt_pk_bf16_f32 v95, v90, v91
	v_cvt_pk_bf16_f32 v87, v82, v83
	v_lshl_add_u64 v[80:81], v[80:81], 0, v[168:169]
	v_cvt_pk_bf16_f32 v76, v76, v77
	v_cvt_pk_bf16_f32 v77, v78, v79
	v_cvt_pk_bf16_f32 v78, v72, v73
	v_cvt_pk_bf16_f32 v79, v74, v75
	v_cvt_pk_bf16_f32 v71, v66, v67
	v_lshl_add_u64 v[64:65], v[64:65], 0, v[168:169]
	v_cvt_pk_bf16_f32 v60, v60, v61
	v_cvt_pk_bf16_f32 v61, v62, v63
	v_cvt_pk_bf16_f32 v62, v56, v57
	v_cvt_pk_bf16_f32 v63, v58, v59
	v_cvt_pk_bf16_f32 v55, v50, v51
	v_lshl_add_u64 v[48:49], v[48:49], 0, v[168:169]
	v_cvt_pk_bf16_f32 v44, v44, v45
	v_cvt_pk_bf16_f32 v45, v46, v47
	v_cvt_pk_bf16_f32 v46, v40, v41
	v_cvt_pk_bf16_f32 v47, v42, v43
	v_cvt_pk_bf16_f32 v39, v34, v35
	v_lshl_add_u64 v[32:33], v[32:33], 0, v[168:169]
	v_cvt_pk_bf16_f32 v28, v28, v29
	v_cvt_pk_bf16_f32 v29, v30, v31
	v_cvt_pk_bf16_f32 v30, v24, v25
	v_cvt_pk_bf16_f32 v31, v26, v27
	v_cvt_pk_bf16_f32 v23, v18, v19
	v_lshl_add_u64 v[16:17], v[16:17], 0, v[168:169]
	v_cvt_pk_bf16_f32 v12, v12, v13
	v_cvt_pk_bf16_f32 v13, v14, v15
	v_cvt_pk_bf16_f32 v14, v8, v9
	v_cvt_pk_bf16_f32 v15, v10, v11
	v_cvt_pk_bf16_f32 v4, v4, v5
	v_cvt_pk_bf16_f32 v5, v6, v7
	v_cvt_pk_bf16_f32 v6, v0, v1
	v_cvt_pk_bf16_f32 v7, v2, v3
	s_and_b64 vcc, exec, s[42:43]
	s_mov_b32 s76, s77
	s_mov_b32 s72, s78
	s_mov_b64 s[46:47], s[44:45]
	s_mov_b64 s[52:53], s[0:1]
	v_lshl_add_u64 v[138:139], s[16:17], 0, v[174:175]
	s_mov_b64 s[26:27], 0x800
	v_lshl_add_u64 v[112:113], v[138:139], 0, s[26:27]
	v_lshl_add_u64 v[96:97], v[112:113], 0, s[26:27]
	v_lshl_add_u64 v[80:81], v[96:97], 0, s[26:27]
	v_lshl_add_u64 v[64:65], v[80:81], 0, s[26:27]
	v_lshl_add_u64 v[48:49], v[64:65], 0, s[26:27]
	v_lshl_add_u64 v[32:33], v[48:49], 0, s[26:27]
	v_lshl_add_u64 v[16:17], v[32:33], 0, s[26:27]
	global_store_dwordx4 v[138:139], v[120:123], off
	global_store_dwordx4 v[138:139], v[116:119], off offset:1024
	global_store_dwordx4 v[112:113], v[108:111], off
	global_store_dwordx4 v[112:113], v[100:103], off offset:1024
	global_store_dwordx4 v[96:97], v[92:95], off
	global_store_dwordx4 v[96:97], v[84:87], off offset:1024
	global_store_dwordx4 v[80:81], v[76:79], off
	global_store_dwordx4 v[80:81], v[68:71], off offset:1024
	global_store_dwordx4 v[64:65], v[60:63], off
	global_store_dwordx4 v[64:65], v[52:55], off offset:1024
	global_store_dwordx4 v[48:49], v[44:47], off
	global_store_dwordx4 v[48:49], v[36:39], off offset:1024
	global_store_dwordx4 v[32:33], v[28:31], off
	global_store_dwordx4 v[32:33], v[20:23], off offset:1024
	global_store_dwordx4 v[16:17], v[12:15], off
	global_store_dwordx4 v[16:17], v[4:7], off offset:1024
	s_cbranch_vccnz .LBB0_168

; __device__ __forceinline__ float bflo(unsigned w) { return __uint_as_float(w << 16); }
; __device__ __forceinline__ float bfhi(unsigned w) { return __uint_as_float(w & 0xffff0000u); }
; __device__ __forceinline__ float fsigmoid(float x) { return __builtin_amdgcn_rcpf(1.0f + __builtin_amdgcn_exp2f(-1.4426950408889634f * x)); }
;     template <int NM> __device__ __forceinline__ void round(const AccT& acc, const Unit& u, int ai, int m0, int wr, int wc, int fr, int fq) const {
;     ...
;             const int rl = ai * 128 + wr * 64 + (m0 + mm) * 16 + fr;
;             const size_t off = (size_t)(u.pm * 256 + rl) * DM + u.pn * 256 + wc * 32 + 8 * fq;
; #pragma unroll
;             for (int bj = 0; bj < 2; ++bj) {
;                 hv[mm][bj] = *GP(const u32x4, hin + off + bj * 128); lv[mm][bj] = (u32x2){0u, 0u};
;                 if (MODE == 1) pv[mm][bj] = *GP(const u32x4, proj + off + bj * 128);
;             }
;         }
; #pragma unroll
;         for (int mm = 0; mm < NM; ++mm) {
;             const int m = m0 + mm;
;             const int rl = ai * 128 + wr * 64 + m * 16 + fr; const int row = u.pm * 256 + rl;
;             const size_t off = (size_t)row * DM + u.pn * 256 + wc * 32 + 8 * fq;
;             float r = 1.f; if (MODE == 1) r = rs[((u.pm >> 3) & 3) * 256 + rl];
;             float ss = 0.f;
; #pragma unroll
;             for (int bj = 0; bj < 2; ++bj) {
;                 f32x4 d0, d1;
;                 if (MODE == 0) { d0 = acc[ai][bj][m][0] * alpha; d1 = acc[ai][bj][m][1] * alpha; }
;                 else {
;                     const u32x4 p = pv[mm][bj];
;                     const f32x4 a0 = acc[ai][bj][m][0] * r, a1 = acc[ai][bj][m][1] * r;
;                     d0 = (f32x4){fsigmoid(a0[0]) * bflo(p.x), fsigmoid(a0[1]) * bfhi(p.x), fsigmoid(a0[2]) * bflo(p.y), fsigmoid(a0[3]) * bfhi(p.y)};
;                     d1 = (f32x4){fsigmoid(a1[0]) * bflo(p.z), fsigmoid(a1[1]) * bfhi(p.z), fsigmoid(a1[2]) * bflo(p.w), fsigmoid(a1[3]) * bfhi(p.w)};
.LBB0_577:
	s_lshl_b32 s26, s81, 2
	s_add_i32 s26, s26, s25
	s_lshl_b32 s26, s26, 17
	s_mov_b32 s27, 0
	v_and_b32_e32 v176, 0xffffffc0, v162
	v_lshlrev_b32_e32 v176, 8, v176
	v_lshl_add_u32 v176, v208, 4, v176
	v_mov_b32_e32 v177, 0
	v_lshl_add_u64 v[176:177], s[26:27], 0, v[176:177]
	v_lshl_add_u64 v[176:177], s[18:19], 0, v[176:177]
	s_lshl_b32 s46, s81, 8
	v_add_u32_e32 v192, s46, v148
	s_lshl_b32 s16, s25, 8
	s_ashr_i32 s17, s16, 31
	v_ashrrev_i32_e32 v193, 31, v192
	v_mov_b32_e32 v159, s17
	v_or_b32_e32 v158, s16, v150
	v_lshlrev_b64 v[128:129], 10, v[192:193]
	v_lshl_add_u64 v[128:129], v[128:129], 0, v[158:159]
	v_lshlrev_b64 v[128:129], 1, v[128:129]
	v_mov_b64_e32 v[130:131], v[176:177]
	v_lshl_add_u64 v[128:129], s[66:67], 0, v[128:129]
	global_load_dwordx4 v[212:215], v[130:131], off
	global_load_dwordx4 v[216:219], v[128:129], off
	s_lshl_b32 s12, s81, 7
	s_and_b32 s12, s12, 0xc00
	s_add_i32 s12, s12, 0
	s_add_i32 s12, s12, 0x20000
	v_lshl_add_u32 v205, v148, 2, s12
	ds_read_b32 v224, v205
	global_load_dwordx4 v[144:147], v[128:129], off offset:256
	global_load_dwordx4 v[220:223], v[130:131], off offset:1024
	v_and_b32_e32 v132, 64, v163
	v_xor_b32_e32 v133, 16, v163
	v_add_u32_e32 v135, 64, v132
	v_or_b32_e32 v132, 16, v192
	v_cmp_lt_i32_e32 vcc, v133, v135
	v_xor_b32_e32 v134, 32, v163
	s_waitcnt lgkmcnt(0)
	v_pk_mul_f32 v[122:123], v[122:123], v[224:225] op_sel_hi:[1,0]
	v_cndmask_b32_e32 v136, v163, v133, vcc
	v_ashrrev_i32_e32 v133, 31, v132
	v_lshlrev_b64 v[132:133], 10, v[132:133]
	v_lshl_add_u64 v[132:133], v[132:133], 0, v[158:159]
	v_cmp_lt_i32_e32 vcc, v134, v135
	v_lshlrev_b64 v[132:133], 1, v[132:133]
	v_lshl_add_u64 v[128:129], s[66:67], 0, v[132:133]
	v_cndmask_b32_e32 v134, v163, v134, vcc
	s_mov_b64 s[26:27], 0x800
	v_lshl_add_u64 v[132:133], v[176:177], 0, s[26:27]
	v_lshlrev_b32_e32 v204, 2, v136
	v_lshlrev_b32_e32 v203, 2, v134
	global_load_dwordx4 v[136:139], v[128:129], off
	s_nop 0
	global_load_dwordx4 v[128:131], v[128:129], off offset:256
	s_nop 0
	global_load_dwordx4 v[140:143], v[132:133], off
	s_nop 0
	global_load_dwordx4 v[132:135], v[132:133], off offset:1024
	v_pk_mul_f32 v[120:121], v[120:121], v[224:225] op_sel_hi:[1,0]
	v_pk_mul_f32 v[126:127], v[126:127], v[224:225] op_sel_hi:[1,0]
	v_pk_mul_f32 v[124:125], v[124:125], v[224:225] op_sel_hi:[1,0]
	v_mul_f32_e32 v120, 0xbfb8aa3b, v120
	v_mul_f32_e32 v121, 0xbfb8aa3b, v121
	v_mul_f32_e32 v122, 0xbfb8aa3b, v122
	v_mul_f32_e32 v123, 0xbfb8aa3b, v123
	v_mul_f32_e32 v124, 0xbfb8aa3b, v124
	v_mul_f32_e32 v125, 0xbfb8aa3b, v125
	v_mul_f32_e32 v126, 0xbfb8aa3b, v126
	v_mul_f32_e32 v127, 0xbfb8aa3b, v127
	v_exp_f32_e32 v120, v120
	v_exp_f32_e32 v121, v121
	v_exp_f32_e32 v122, v122
	v_exp_f32_e32 v123, v123
	v_exp_f32_e32 v124, v124
	v_exp_f32_e32 v125, v125
	v_exp_f32_e32 v126, v126
	v_exp_f32_e32 v127, v127
	v_add_f32_e32 v120, 1.0, v120
	v_add_f32_e32 v121, 1.0, v121
	v_add_f32_e32 v122, 1.0, v122
	v_add_f32_e32 v123, 1.0, v123
	v_add_f32_e32 v124, 1.0, v124
	v_add_f32_e32 v125, 1.0, v125
	v_add_f32_e32 v126, 1.0, v126
	v_add_f32_e32 v127, 1.0, v127
	v_rcp_f32_e32 v226, v120
	v_rcp_f32_e32 v227, v121
	v_rcp_f32_e32 v228, v122
	v_rcp_f32_e32 v229, v123
	v_cvt_pk_f32_fp8_e32 v[120:121], 0
	v_cvt_pk_f32_fp8_sdwa v[122:123], s63 src0_sel:WORD_1
	v_rcp_f32_e32 v124, v124
	v_rcp_f32_e32 v125, v125
	v_rcp_f32_e32 v126, v126
	v_rcp_f32_e32 v127, v127
	v_pk_mul_f32 v[118:119], v[118:119], v[224:225] op_sel_hi:[1,0]
	v_pk_mul_f32 v[116:117], v[116:117], v[224:225] op_sel_hi:[1,0]
	v_mul_f32_e32 v118, 0xbfb8aa3b, v118
	v_mul_f32_e32 v119, 0xbfb8aa3b, v119
	v_mul_f32_e32 v116, 0xbfb8aa3b, v116
	v_mul_f32_e32 v117, 0xbfb8aa3b, v117
	v_pk_mul_f32 v[112:113], v[112:113], v[224:225] op_sel_hi:[1,0]
	v_exp_f32_e32 v118, v118
	v_exp_f32_e32 v119, v119
	v_exp_f32_e32 v116, v116
	v_exp_f32_e32 v117, v117
	v_mul_f32_e32 v112, 0xbfb8aa3b, v112
	v_mul_f32_e32 v113, 0xbfb8aa3b, v113
	v_exp_f32_e32 v112, v112
	v_exp_f32_e32 v113, v113
	s_waitcnt vmcnt(0)
; __device__ __forceinline__ unsigned cvt_pk_bf16(float lo, float hi) { const f32x2 v = {lo, hi}; return __builtin_bit_cast(unsigned, __builtin_convertvector(v, bfx2_t)); }
; __device__ __forceinline__ float bflo(unsigned w) { return __uint_as_float(w << 16); }
; __device__ __forceinline__ float bfhi(unsigned w) { return __uint_as_float(w & 0xffff0000u); }
; __device__ __forceinline__ unsigned lo_pack4(float a, float b, float c, float d) { int p = __builtin_amdgcn_cvt_pk_fp8_f32(a * 512.0f, b * 512.0f, 0, false); return (unsigned)__builtin_amdgcn_cvt_pk_fp8_f32(c * 512.0f, d * 512.0f, p, true); }
; __device__ __forceinline__ f32x4 lo_unpack4(unsigned w) { const f32x2 a = __builtin_amdgcn_cvt_pk_f32_fp8((int)w, false), b = __builtin_amdgcn_cvt_pk_f32_fp8((int)w, true); return (f32x4){a.x, a.y, b.x, b.y} * (1.0f / 512.0f); }
;     template <int NM> __device__ __forceinline__ void round(const AccT& acc, const Unit& u, int ai, int m0, int wr, int wc, int fr, int fq) const {
;     ...
;                 const u32x4 H = hv[mm][bj]; const u32x2 L = lv[mm][bj];
;                 const f32x4 o0 = ((f32x4){bflo(H.x), bfhi(H.x), bflo(H.y), bfhi(H.y)} + lo_unpack4(L.x)) + d0;
;                 const f32x4 o1 = ((f32x4){bflo(H.z), bfhi(H.z), bflo(H.w), bfhi(H.w)} + lo_unpack4(L.y)) + d1;
;                 u32x4 w; w.x = cvt_pk_bf16(o0[0], o0[1]); w.y = cvt_pk_bf16(o0[2], o0[3]); w.z = cvt_pk_bf16(o1[0], o1[1]); w.w = cvt_pk_bf16(o1[2], o1[3]);
;                 u32x2 wl; wl.x = lo_pack4(o0[0] - bflo(w.x), o0[1] - bfhi(w.x), o0[2] - bflo(w.y), o0[3] - bfhi(w.y));
;                 wl.y = lo_pack4(o1[0] - bflo(w.z), o1[1] - bfhi(w.z), o1[2] - bflo(w.w), o1[3] - bfhi(w.w));
;                 *GP(u32x4, hout + off + bj * 128) = w; (void)wl;
;                 ss += (o0[0] * o0[0] + o0[1] * o0[1]) + (o0[2] * o0[2] + o0[3] * o0[3]) + (o1[0] * o1[0] + o1[1] * o1[1]) + (o1[2] * o1[2] + o1[3] * o1[3]);
;             }
;             ss += __shfl_xor(ss, 16); ss += __shfl_xor(ss, 32);
;             if (fq == 0) *GP(float, ssp + (size_t)(u.pn * 4 + wc) * TT + row) = ss;
	v_lshlrev_b32_e32 v230, 16, v212
	v_lshlrev_b32_e32 v234, 16, v216
	v_and_b32_e32 v235, 0xffff0000, v216
	v_lshlrev_b32_e32 v216, 16, v217
	v_and_b32_e32 v217, 0xffff0000, v217
	v_and_b32_e32 v231, 0xffff0000, v212
	v_lshlrev_b32_e32 v212, 16, v213
	v_and_b32_e32 v213, 0xffff0000, v213
	v_pk_fma_f32 v[234:235], v[120:121], s[34:35], v[234:235] op_sel_hi:[1,0,1]
	v_pk_fma_f32 v[216:217], v[122:123], s[34:35], v[216:217] op_sel_hi:[1,0,1]
	v_lshlrev_b32_e32 v232, 16, v214
	v_pk_fma_f32 v[212:213], v[126:127], v[212:213], v[216:217]
	v_pk_fma_f32 v[216:217], v[124:125], v[230:231], v[234:235]
	v_lshlrev_b32_e32 v124, 16, v218
	v_and_b32_e32 v125, 0xffff0000, v218
	v_and_b32_e32 v233, 0xffff0000, v214
	v_pk_fma_f32 v[124:125], v[120:121], s[34:35], v[124:125] op_sel_hi:[1,0,1]
	v_lshlrev_b32_e32 v126, 16, v219
	v_and_b32_e32 v127, 0xffff0000, v219
	v_pk_fma_f32 v[218:219], v[226:227], v[232:233], v[124:125]
	v_cvt_pk_bf16_f32 v125, v212, v213
	v_mul_f32_e32 v211, v217, v217
	v_mul_f32_e32 v213, v213, v213
	v_lshlrev_b32_e32 v214, 16, v215
	v_and_b32_e32 v215, 0xffff0000, v215
	v_pk_fma_f32 v[126:127], v[122:123], s[34:35], v[126:127] op_sel_hi:[1,0,1]
	v_fmac_f32_e32 v211, v216, v216
	v_fmac_f32_e32 v213, v212, v212
	v_mul_f32_e32 v212, v219, v219
	v_pk_mul_f32 v[114:115], v[114:115], v[224:225] op_sel_hi:[1,0]
	v_pk_fma_f32 v[214:215], v[228:229], v[214:215], v[126:127]
	v_add_f32_e32 v211, v211, v213
	v_fmac_f32_e32 v212, v218, v218
	v_add_f32_e32 v118, 1.0, v118
	v_add_f32_e32 v119, 1.0, v119
	v_mul_f32_e32 v114, 0xbfb8aa3b, v114
	v_mul_f32_e32 v115, 0xbfb8aa3b, v115
	v_add_f32_e32 v211, v212, v211
	v_mul_f32_e32 v212, v215, v215
	v_add_f32_e32 v116, 1.0, v116
	v_add_f32_e32 v117, 1.0, v117
	v_rcp_f32_e32 v118, v118
	v_rcp_f32_e32 v119, v119
	v_exp_f32_e32 v114, v114
	v_exp_f32_e32 v115, v115
	v_fmac_f32_e32 v212, v214, v214
	v_rcp_f32_e32 v116, v116
	v_rcp_f32_e32 v117, v117
	v_add_f32_e32 v112, 1.0, v112
	v_add_f32_e32 v113, 1.0, v113
	v_cvt_pk_bf16_f32 v127, v214, v215
	v_add_f32_e32 v211, v212, v211
	v_lshlrev_b32_e32 v212, 16, v220
	v_and_b32_e32 v213, 0xffff0000, v220
	v_lshlrev_b32_e32 v214, 16, v221
	v_and_b32_e32 v215, 0xffff0000, v221
	v_rcp_f32_e32 v112, v112
	v_rcp_f32_e32 v113, v113
	v_lshlrev_b32_e32 v220, 16, v144
	v_and_b32_e32 v221, 0xffff0000, v144
	v_lshlrev_b32_e32 v144, 16, v145
	v_and_b32_e32 v145, 0xffff0000, v145
	v_pk_fma_f32 v[144:145], v[122:123], s[34:35], v[144:145] op_sel_hi:[1,0,1]
	v_add_f32_e32 v114, 1.0, v114
	v_add_f32_e32 v115, 1.0, v115
	v_pk_fma_f32 v[220:221], v[120:121], s[34:35], v[220:221] op_sel_hi:[1,0,1]
	v_pk_fma_f32 v[118:119], v[118:119], v[214:215], v[144:145]
	v_lshlrev_b32_e32 v144, 16, v146
	v_and_b32_e32 v145, 0xffff0000, v146
	v_cvt_pk_bf16_f32 v124, v216, v217
	v_lshlrev_b32_e32 v216, 16, v222
	v_and_b32_e32 v217, 0xffff0000, v222
	v_rcp_f32_e32 v114, v114
	v_rcp_f32_e32 v115, v115
	v_pk_fma_f32 v[116:117], v[116:117], v[212:213], v[220:221]
	v_pk_fma_f32 v[144:145], v[120:121], s[34:35], v[144:145] op_sel_hi:[1,0,1]
	v_lshlrev_b32_e32 v146, 16, v147
	v_pk_fma_f32 v[144:145], v[112:113], v[216:217], v[144:145]
	v_mul_f32_e32 v112, v117, v117
	v_mul_f32_e32 v113, v119, v119
	v_and_b32_e32 v147, 0xffff0000, v147
	v_fmac_f32_e32 v112, v116, v116
	v_fmac_f32_e32 v113, v118, v118
	v_cvt_pk_bf16_f32 v126, v218, v219
	v_lshlrev_b32_e32 v218, 16, v223
	v_and_b32_e32 v219, 0xffff0000, v223
	v_pk_fma_f32 v[146:147], v[122:123], s[34:35], v[146:147] op_sel_hi:[1,0,1]
	v_add_f32_e32 v112, v112, v113
	v_mul_f32_e32 v113, v145, v145
	v_pk_fma_f32 v[146:147], v[114:115], v[218:219], v[146:147]
	v_fmac_f32_e32 v113, v144, v144
	v_add_f32_e32 v112, v113, v112
	v_mul_f32_e32 v113, v147, v147
	v_fmac_f32_e32 v113, v146, v146
	v_add_f32_e32 v112, v113, v112
	v_add_f32_e32 v115, v211, v112
	ds_bpermute_b32 v211, v204, v115
	v_lshlrev_b64 v[206:207], 11, v[192:193]
	v_lshl_add_u64 v[206:207], s[14:15], 0, v[206:207]
	v_lshl_add_u64 v[206:207], s[16:17], 1, v[206:207]
	v_lshl_add_u64 v[112:113], v[206:207], 0, s[62:63]
	v_lshl_add_u64 v[206:207], v[112:113], 0, v[168:169]
	s_waitcnt lgkmcnt(0)
	v_add_f32_e32 v112, v115, v211
	ds_bpermute_b32 v113, v203, v112
	v_cvt_pk_bf16_f32 v114, v116, v117
	v_cvt_pk_bf16_f32 v115, v118, v119
	v_cvt_pk_bf16_f32 v116, v144, v145
	v_cvt_pk_bf16_f32 v117, v146, v147
	global_store_dwordx4 v[206:207], v[124:127], off
	global_store_dwordx4 v[206:207], v[114:117], off offset:256
	s_and_saveexec_b64 s[12:13], s[42:43]
	s_cbranch_execz .LBB0_579
	s_lshl_b32 s20, s25, 2
	s_or_b32 s20, s20, s71
	s_ashr_i32 s21, s20, 31
	s_lshl_b64 s[20:21], s[20:21], 18
	s_add_u32 s20, s65, s20
	s_addc_u32 s21, s70, s21
	s_waitcnt lgkmcnt(0)
	v_add_f32_e32 v114, v112, v113
	v_lshl_add_u64 v[112:113], v[192:193], 2, s[20:21]
	global_store_dword v[112:113], v114, off

; __device__ __forceinline__ float bflo(unsigned w) { return __uint_as_float(w << 16); }
; __device__ __forceinline__ float bfhi(unsigned w) { return __uint_as_float(w & 0xffff0000u); }
; __device__ __forceinline__ float fsigmoid(float x) { return __builtin_amdgcn_rcpf(1.0f + __builtin_amdgcn_exp2f(-1.4426950408889634f * x)); }
;     template <int NM> __device__ __forceinline__ void round(const AccT& acc, const Unit& u, int ai, int m0, int wr, int wc, int fr, int fq) const {
;     ...
;             const int rl = ai * 128 + wr * 64 + (m0 + mm) * 16 + fr;
;             const size_t off = (size_t)(u.pm * 256 + rl) * DM + u.pn * 256 + wc * 32 + 8 * fq;
; #pragma unroll
;             for (int bj = 0; bj < 2; ++bj) {
;                 hv[mm][bj] = *GP(const u32x4, hin + off + bj * 128); lv[mm][bj] = (u32x2){0u, 0u};
;                 if (MODE == 1) pv[mm][bj] = *GP(const u32x4, proj + off + bj * 128);
;             }
;         }
; #pragma unroll
;         for (int mm = 0; mm < NM; ++mm) {
;             const int m = m0 + mm;
;             const int rl = ai * 128 + wr * 64 + m * 16 + fr; const int row = u.pm * 256 + rl;
;             const size_t off = (size_t)row * DM + u.pn * 256 + wc * 32 + 8 * fq;
;             float r = 1.f; if (MODE == 1) r = rs[((u.pm >> 3) & 3) * 256 + rl];
;             float ss = 0.f;
; #pragma unroll
;             for (int bj = 0; bj < 2; ++bj) {
;                 f32x4 d0, d1;
;                 if (MODE == 0) { d0 = acc[ai][bj][m][0] * alpha; d1 = acc[ai][bj][m][1] * alpha; }
;                 else {
;                     const u32x4 p = pv[mm][bj];
;                     const f32x4 a0 = acc[ai][bj][m][0] * r, a1 = acc[ai][bj][m][1] * r;
;                     d0 = (f32x4){fsigmoid(a0[0]) * bflo(p.x), fsigmoid(a0[1]) * bfhi(p.x), fsigmoid(a0[2]) * bflo(p.y), fsigmoid(a0[3]) * bfhi(p.y)};
;                     d1 = (f32x4){fsigmoid(a1[0]) * bflo(p.z), fsigmoid(a1[1]) * bfhi(p.z), fsigmoid(a1[2]) * bflo(p.w), fsigmoid(a1[3]) * bfhi(p.w)};
.LBB0_581:
	s_or_b64 exec, exec, s[12:13]
	v_or_b32_e32 v96, 32, v192
	s_waitcnt lgkmcnt(0)
	v_ashrrev_i32_e32 v97, 31, v96
	v_lshlrev_b64 v[96:97], 10, v[96:97]
	v_lshl_add_u64 v[96:97], v[96:97], 0, v[158:159]
	v_lshlrev_b64 v[96:97], 1, v[96:97]
	v_lshl_add_u64 v[98:99], s[66:67], 0, v[96:97]
	s_mov_b64 s[26:27], 0x1000
	v_lshl_add_u64 v[96:97], v[176:177], 0, s[26:27]
	global_load_dwordx4 v[120:123], v[98:99], off
	global_load_dwordx4 v[124:127], v[96:97], off
	global_load_dwordx4 v[112:115], v[98:99], off offset:256
	global_load_dwordx4 v[116:119], v[96:97], off offset:1024
	v_or_b32_e32 v96, 48, v192
	v_ashrrev_i32_e32 v97, 31, v96
	v_lshlrev_b64 v[96:97], 10, v[96:97]
	v_lshl_add_u64 v[96:97], v[96:97], 0, v[158:159]
	v_lshlrev_b64 v[96:97], 1, v[96:97]
	v_lshl_add_u64 v[98:99], s[66:67], 0, v[96:97]
	s_mov_b64 s[26:27], 0x1800
	v_lshl_add_u64 v[100:101], v[176:177], 0, s[26:27]
	global_load_dwordx4 v[104:107], v[98:99], off
	global_load_dwordx4 v[108:111], v[100:101], off
	s_nop 0
	global_load_dwordx4 v[96:99], v[98:99], off offset:256
	s_nop 0
	global_load_dwordx4 v[100:103], v[100:101], off offset:1024
	ds_read_b32 v128, v205 offset:128
	v_add_u32_e32 v130, s46, v154
	v_ashrrev_i32_e32 v131, 31, v130
	v_lshlrev_b64 v[130:131], 11, v[130:131]
	s_waitcnt lgkmcnt(0)
	v_pk_mul_f32 v[94:95], v[94:95], v[128:129] op_sel_hi:[1,0]
	v_pk_mul_f32 v[92:93], v[92:93], v[128:129] op_sel_hi:[1,0]
	v_pk_mul_f32 v[132:133], v[90:91], v[128:129] op_sel_hi:[1,0]
	v_pk_mul_f32 v[134:135], v[88:89], v[128:129] op_sel_hi:[1,0]
	v_mul_f32_e32 v88, 0xbfb8aa3b, v92
	v_mul_f32_e32 v89, 0xbfb8aa3b, v93
	v_mul_f32_e32 v92, 0xbfb8aa3b, v94
	v_mul_f32_e32 v93, 0xbfb8aa3b, v95
	v_exp_f32_e32 v88, v88
	v_exp_f32_e32 v89, v89
	v_exp_f32_e32 v92, v92
	v_exp_f32_e32 v93, v93
	v_add_f32_e32 v88, 1.0, v88
	v_add_f32_e32 v89, 1.0, v89
	v_rcp_f32_e32 v88, v88
	v_rcp_f32_e32 v89, v89
	v_add_f32_e32 v92, 1.0, v92
	v_add_f32_e32 v93, 1.0, v93
	v_rcp_f32_e32 v92, v92
	v_rcp_f32_e32 v93, v93
	v_pk_mul_f32 v[86:87], v[86:87], v[128:129] op_sel_hi:[1,0]
	v_pk_mul_f32 v[84:85], v[84:85], v[128:129] op_sel_hi:[1,0]
	v_mul_f32_e32 v86, 0xbfb8aa3b, v86
	v_mul_f32_e32 v84, 0xbfb8aa3b, v84
	v_mul_f32_e32 v85, 0xbfb8aa3b, v85
	v_mul_f32_e32 v87, 0xbfb8aa3b, v87
	v_pk_mul_f32 v[82:83], v[82:83], v[128:129] op_sel_hi:[1,0]
	v_pk_mul_f32 v[80:81], v[80:81], v[128:129] op_sel_hi:[1,0]
	v_exp_f32_e32 v84, v84
	v_exp_f32_e32 v85, v85
	v_exp_f32_e32 v86, v86
	v_exp_f32_e32 v87, v87
	v_mul_f32_e32 v80, 0xbfb8aa3b, v80
	v_mul_f32_e32 v81, 0xbfb8aa3b, v81
	v_mul_f32_e32 v82, 0xbfb8aa3b, v82
	v_mul_f32_e32 v83, 0xbfb8aa3b, v83
	v_exp_f32_e32 v80, v80
	v_exp_f32_e32 v81, v81
	v_exp_f32_e32 v82, v82
	v_exp_f32_e32 v83, v83
	v_add_f32_e32 v84, 1.0, v84
	v_add_f32_e32 v85, 1.0, v85
	v_add_f32_e32 v86, 1.0, v86
	v_add_f32_e32 v87, 1.0, v87
	v_rcp_f32_e32 v84, v84
	v_rcp_f32_e32 v85, v85
	v_rcp_f32_e32 v86, v86
	v_rcp_f32_e32 v87, v87
	v_add_f32_e32 v80, 1.0, v80
	v_add_f32_e32 v81, 1.0, v81
	v_add_f32_e32 v82, 1.0, v82
	v_add_f32_e32 v83, 1.0, v83
	v_rcp_f32_e32 v80, v80
	v_rcp_f32_e32 v81, v81
	v_rcp_f32_e32 v82, v82
	v_rcp_f32_e32 v83, v83
	s_waitcnt vmcnt(7)
	v_lshlrev_b32_e32 v136, 16, v120
	s_waitcnt vmcnt(6)
; __device__ __forceinline__ unsigned cvt_pk_bf16(float lo, float hi) { const f32x2 v = {lo, hi}; return __builtin_bit_cast(unsigned, __builtin_convertvector(v, bfx2_t)); }
; __device__ __forceinline__ float bflo(unsigned w) { return __uint_as_float(w << 16); }
; __device__ __forceinline__ float bfhi(unsigned w) { return __uint_as_float(w & 0xffff0000u); }
; __device__ __forceinline__ unsigned lo_pack4(float a, float b, float c, float d) { int p = __builtin_amdgcn_cvt_pk_fp8_f32(a * 512.0f, b * 512.0f, 0, false); return (unsigned)__builtin_amdgcn_cvt_pk_fp8_f32(c * 512.0f, d * 512.0f, p, true); }
; __device__ __forceinline__ f32x4 lo_unpack4(unsigned w) { const f32x2 a = __builtin_amdgcn_cvt_pk_f32_fp8((int)w, false), b = __builtin_amdgcn_cvt_pk_f32_fp8((int)w, true); return (f32x4){a.x, a.y, b.x, b.y} * (1.0f / 512.0f); }
;     template <int NM> __device__ __forceinline__ void round(const AccT& acc, const Unit& u, int ai, int m0, int wr, int wc, int fr, int fq) const {
;     ...
;                 const u32x4 H = hv[mm][bj]; const u32x2 L = lv[mm][bj];
;                 const f32x4 o0 = ((f32x4){bflo(H.x), bfhi(H.x), bflo(H.y), bfhi(H.y)} + lo_unpack4(L.x)) + d0;
;                 const f32x4 o1 = ((f32x4){bflo(H.z), bfhi(H.z), bflo(H.w), bfhi(H.w)} + lo_unpack4(L.y)) + d1;
;                 u32x4 w; w.x = cvt_pk_bf16(o0[0], o0[1]); w.y = cvt_pk_bf16(o0[2], o0[3]); w.z = cvt_pk_bf16(o1[0], o1[1]); w.w = cvt_pk_bf16(o1[2], o1[3]);
;                 u32x2 wl; wl.x = lo_pack4(o0[0] - bflo(w.x), o0[1] - bfhi(w.x), o0[2] - bflo(w.y), o0[3] - bfhi(w.y));
;                 wl.y = lo_pack4(o1[0] - bflo(w.z), o1[1] - bfhi(w.z), o1[2] - bflo(w.w), o1[3] - bfhi(w.w));
;                 *GP(u32x4, hout + off + bj * 128) = w; (void)wl;
;                 ss += (o0[0] * o0[0] + o0[1] * o0[1]) + (o0[2] * o0[2] + o0[3] * o0[3]) + (o1[0] * o1[0] + o1[1] * o1[1]) + (o1[2] * o1[2] + o1[3] * o1[3]);
;             }
;             ss += __shfl_xor(ss, 16); ss += __shfl_xor(ss, 32);
;             if (fq == 0) *GP(float, ssp + (size_t)(u.pn * 4 + wc) * TT + row) = ss;
	v_lshlrev_b32_e32 v90, 16, v124
	v_and_b32_e32 v91, 0xffff0000, v124
	v_lshlrev_b32_e32 v94, 16, v125
	v_and_b32_e32 v95, 0xffff0000, v125
	v_mul_f32_e32 v124, 0xbfb8aa3b, v134
	v_mul_f32_e32 v125, 0xbfb8aa3b, v135
	v_lshlrev_b32_e32 v134, 16, v126
	v_and_b32_e32 v135, 0xffff0000, v126
	v_mul_f32_e32 v126, 0xbfb8aa3b, v132
	v_exp_f32_e32 v126, v126
	v_exp_f32_e32 v124, v124
	v_exp_f32_e32 v125, v125
	v_and_b32_e32 v137, 0xffff0000, v120
	v_add_f32_e32 v126, 1.0, v126
	v_rcp_f32_e32 v132, v126
	v_mul_f32_e32 v126, 0xbfb8aa3b, v133
	v_exp_f32_e32 v126, v126
	v_add_f32_e32 v124, 1.0, v124
	v_add_f32_e32 v125, 1.0, v125
	v_rcp_f32_e32 v124, v124
	v_add_f32_e32 v126, 1.0, v126
	v_rcp_f32_e32 v125, v125
	v_rcp_f32_e32 v133, v126
	v_pk_add_f32 v[136:137], v[146:147], v[136:137]
	v_lshlrev_b32_e32 v120, 16, v121
	v_and_b32_e32 v121, 0xffff0000, v121
	v_pk_fma_f32 v[136:137], v[88:89], v[90:91], v[136:137]
	v_lshlrev_b32_e32 v88, 16, v122
	v_and_b32_e32 v89, 0xffff0000, v122
	v_lshlrev_b32_e32 v90, 16, v123
	v_and_b32_e32 v91, 0xffff0000, v123
	v_lshl_add_u64 v[122:123], s[14:15], 0, v[130:131]
	v_lshlrev_b32_e32 v126, 16, v127
	v_and_b32_e32 v127, 0xffff0000, v127
	v_pk_add_f32 v[120:121], v[144:145], v[120:121]
	v_pk_add_f32 v[90:91], v[144:145], v[90:91]
	v_pk_add_f32 v[88:89], v[146:147], v[88:89]
	v_lshl_add_u64 v[122:123], s[16:17], 1, v[122:123]
	v_pk_fma_f32 v[92:93], v[92:93], v[94:95], v[120:121]
	v_pk_fma_f32 v[94:95], v[124:125], v[134:135], v[88:89]
	v_pk_fma_f32 v[120:121], v[132:133], v[126:127], v[90:91]
	v_lshl_add_u64 v[122:123], v[122:123], 0, s[62:63]
	v_cvt_pk_bf16_f32 v88, v136, v137
	v_cvt_pk_bf16_f32 v89, v92, v93
	v_cvt_pk_bf16_f32 v90, v94, v95
	v_cvt_pk_bf16_f32 v91, v120, v121
	v_lshl_add_u64 v[122:123], v[122:123], 0, v[168:169]
	global_store_dwordx4 v[122:123], v[88:91], off
	s_nop 1
	v_mul_f32_e32 v88, v137, v137
	v_mul_f32_e32 v89, v93, v93
	v_fmac_f32_e32 v88, v136, v136
	v_fmac_f32_e32 v89, v92, v92
	v_add_f32_e32 v88, v88, v89
	v_mul_f32_e32 v89, v95, v95
	v_fmac_f32_e32 v89, v94, v94
	v_add_f32_e32 v88, v89, v88
	v_mul_f32_e32 v89, v121, v121
	v_fmac_f32_e32 v89, v120, v120
	v_add_f32_e32 v120, v89, v88
	s_waitcnt vmcnt(5)
	v_lshlrev_b32_e32 v88, 16, v116
	v_and_b32_e32 v89, 0xffff0000, v116
	v_lshlrev_b32_e32 v90, 16, v117
	v_and_b32_e32 v91, 0xffff0000, v117
	v_lshlrev_b32_e32 v116, 16, v112
	v_and_b32_e32 v117, 0xffff0000, v112
	v_lshlrev_b32_e32 v112, 16, v113
	v_and_b32_e32 v113, 0xffff0000, v113
	v_pk_add_f32 v[112:113], v[144:145], v[112:113]
	v_pk_add_f32 v[116:117], v[146:147], v[116:117]
	v_pk_fma_f32 v[86:87], v[86:87], v[90:91], v[112:113]
	v_pk_fma_f32 v[84:85], v[84:85], v[88:89], v[116:117]
	v_lshlrev_b32_e32 v88, 16, v114
	v_and_b32_e32 v89, 0xffff0000, v114
	v_lshlrev_b32_e32 v90, 16, v115
	v_and_b32_e32 v91, 0xffff0000, v115
	v_lshlrev_b32_e32 v92, 16, v118
	v_and_b32_e32 v93, 0xffff0000, v118
	v_lshlrev_b32_e32 v94, 16, v119
	v_and_b32_e32 v95, 0xffff0000, v119
	v_pk_add_f32 v[90:91], v[144:145], v[90:91]
	v_pk_add_f32 v[88:89], v[146:147], v[88:89]
	v_pk_fma_f32 v[90:91], v[82:83], v[94:95], v[90:91]
	v_pk_fma_f32 v[88:89], v[80:81], v[92:93], v[88:89]
	v_cvt_pk_bf16_f32 v80, v84, v85
	v_cvt_pk_bf16_f32 v81, v86, v87
	v_cvt_pk_bf16_f32 v82, v88, v89
	v_cvt_pk_bf16_f32 v83, v90, v91
	global_store_dwordx4 v[122:123], v[80:83], off offset:256
	s_nop 1
	v_mul_f32_e32 v80, v85, v85
	v_mul_f32_e32 v81, v87, v87
	v_fmac_f32_e32 v80, v84, v84
	v_fmac_f32_e32 v81, v86, v86
	v_add_f32_e32 v80, v80, v81
	v_mul_f32_e32 v81, v89, v89
	v_fmac_f32_e32 v81, v88, v88
	v_add_f32_e32 v80, v81, v80
	v_mul_f32_e32 v81, v91, v91
	v_fmac_f32_e32 v81, v90, v90
	v_add_f32_e32 v80, v81, v80
	v_add_f32_e32 v80, v120, v80
	ds_bpermute_b32 v81, v204, v80
	s_waitcnt lgkmcnt(0)
	v_add_f32_e32 v80, v80, v81
	ds_bpermute_b32 v81, v203, v80
	s_and_saveexec_b64 s[12:13], s[42:43]
	s_cbranch_execz .LBB0_583
	s_lshl_b32 s20, s25, 2
	s_or_b32 s20, s20, s71
	s_ashr_i32 s21, s20, 31
	s_lshl_b64 s[20:21], s[20:21], 18
	s_add_u32 s20, s65, s20
	s_addc_u32 s21, s70, s21
	s_ashr_i32 s47, s46, 31
	s_waitcnt lgkmcnt(0)
	v_add_f32_e32 v82, v80, v81
	v_lshl_add_u64 v[80:81], s[46:47], 0, v[148:149]
	v_lshl_add_u64 v[80:81], v[80:81], 2, s[20:21]
	global_store_dword v[80:81], v82, off offset:128

;     template <int NM> __device__ __forceinline__ void round(const AccT& acc, const Unit& u, int ai, int m0, int wr, int wc, int fr, int fq) const {
;     ...
;             const int rl = ai * 128 + wr * 64 + (m0 + mm) * 16 + fr;
;             const size_t off = (size_t)(u.pm * 256 + rl) * DM + u.pn * 256 + wc * 32 + 8 * fq;
; #pragma unroll
;             for (int bj = 0; bj < 2; ++bj) {
;                 hv[mm][bj] = *GP(const u32x4, hin + off + bj * 128); lv[mm][bj] = (u32x2){0u, 0u};
;                 if (MODE == 1) pv[mm][bj] = *GP(const u32x4, proj + off + bj * 128);
;             }
;         }
; #pragma unroll
;         for (int mm = 0; mm < NM; ++mm) {
;             const int m = m0 + mm;
;             const int rl = ai * 128 + wr * 64 + m * 16 + fr; const int row = u.pm * 256 + rl;
;             const size_t off = (size_t)row * DM + u.pn * 256 + wc * 32 + 8 * fq;
;             float r = 1.f; if (MODE == 1) r = rs[((u.pm >> 3) & 3) * 256 + rl];
;             float ss = 0.f;
; #pragma unroll
;             for (int bj = 0; bj < 2; ++bj) {
;                 f32x4 d0, d1;
;                 if (MODE == 0) { d0 = acc[ai][bj][m][0] * alpha; d1 = acc[ai][bj][m][1] * alpha; }
;                 else {
;                     const u32x4 p = pv[mm][bj];
;                     const f32x4 a0 = acc[ai][bj][m][0] * r, a1 = acc[ai][bj][m][1] * r;
;                     d0 = (f32x4){fsigmoid(a0[0]) * bflo(p.x), fsigmoid(a0[1]) * bfhi(p.x), fsigmoid(a0[2]) * bflo(p.y), fsigmoid(a0[3]) * bfhi(p.y)};
;                     d1 = (f32x4){fsigmoid(a1[0]) * bflo(p.z), fsigmoid(a1[1]) * bfhi(p.z), fsigmoid(a1[2]) * bflo(p.w), fsigmoid(a1[3]) * bfhi(p.w)};
;                 }
;                 const u32x4 H = hv[mm][bj]; const u32x2 L = lv[mm][bj];
;                 const f32x4 o0 = ((f32x4){bflo(H.x), bfhi(H.x), bflo(H.y), bfhi(H.y)} + lo_unpack4(L.x)) + d0;
;                 const f32x4 o1 = ((f32x4){bflo(H.z), bfhi(H.z), bflo(H.w), bfhi(H.w)} + lo_unpack4(L.y)) + d1;
;                 u32x4 w; w.x = cvt_pk_bf16(o0[0], o0[1]); w.y = cvt_pk_bf16(o0[2], o0[3]); w.z = cvt_pk_bf16(o1[0], o1[1]); w.w = cvt_pk_bf16(o1[2], o1[3]);
;                 u32x2 wl; wl.x = lo_pack4(o0[0] - bflo(w.x), o0[1] - bfhi(w.x), o0[2] - bflo(w.y), o0[3] - bfhi(w.y));
;                 wl.y = lo_pack4(o1[0] - bflo(w.z), o1[1] - bfhi(w.z), o1[2] - bflo(w.w), o1[3] - bfhi(w.w));
.LBB0_585:
	s_or_b64 exec, exec, s[12:13]
	v_add_u32_e32 v88, s46, v198
	v_ashrrev_i32_e32 v89, 31, v88
	s_waitcnt lgkmcnt(0)
	v_lshlrev_b64 v[64:65], 10, v[88:89]
	v_lshl_add_u64 v[64:65], v[64:65], 0, v[158:159]
	v_lshlrev_b64 v[64:65], 1, v[64:65]
	v_lshl_add_u64 v[66:67], s[66:67], 0, v[64:65]
	s_mov_b64 s[26:27], 0x2000
	v_lshl_add_u64 v[64:65], v[176:177], 0, s[26:27]
	global_load_dwordx4 v[92:95], v[66:67], off
	global_load_dwordx4 v[98:101], v[64:65], off
	global_load_dwordx4 v[80:83], v[66:67], off offset:256
	global_load_dwordx4 v[84:87], v[64:65], off offset:1024
	v_or_b32_e32 v64, 16, v88
	v_ashrrev_i32_e32 v65, 31, v64
	v_lshlrev_b64 v[64:65], 10, v[64:65]
	v_lshl_add_u64 v[64:65], v[64:65], 0, v[158:159]
	v_lshlrev_b64 v[64:65], 1, v[64:65]
	v_lshl_add_u64 v[66:67], s[66:67], 0, v[64:65]
	s_mov_b64 s[26:27], 0x2800
	v_lshl_add_u64 v[68:69], v[176:177], 0, s[26:27]
	global_load_dwordx4 v[72:75], v[66:67], off
	global_load_dwordx4 v[76:79], v[68:69], off
	s_nop 0
	global_load_dwordx4 v[64:67], v[66:67], off offset:256
	s_nop 0
	global_load_dwordx4 v[68:71], v[68:69], off offset:1024
	ds_read_b32 v90, v205 offset:512
	v_lshlrev_b64 v[96:97], 11, v[88:89]
	v_lshl_add_u64 v[96:97], s[14:15], 0, v[96:97]
	v_lshl_add_u64 v[96:97], s[16:17], 1, v[96:97]
	v_lshl_add_u64 v[96:97], v[96:97], 0, s[62:63]
	s_waitcnt lgkmcnt(0)
	v_pk_mul_f32 v[62:63], v[62:63], v[90:91] op_sel_hi:[1,0]
	v_pk_mul_f32 v[60:61], v[60:61], v[90:91] op_sel_hi:[1,0]
	v_mul_f32_e32 v62, 0xbfb8aa3b, v62
	v_mul_f32_e32 v60, 0xbfb8aa3b, v60
	v_mul_f32_e32 v61, 0xbfb8aa3b, v61
	v_mul_f32_e32 v63, 0xbfb8aa3b, v63
	v_pk_mul_f32 v[58:59], v[58:59], v[90:91] op_sel_hi:[1,0]
	v_pk_mul_f32 v[56:57], v[56:57], v[90:91] op_sel_hi:[1,0]
	v_exp_f32_e32 v60, v60
	v_exp_f32_e32 v61, v61
	v_exp_f32_e32 v62, v62
	v_exp_f32_e32 v63, v63
	v_mul_f32_e32 v56, 0xbfb8aa3b, v56
	v_mul_f32_e32 v57, 0xbfb8aa3b, v57
	v_mul_f32_e32 v58, 0xbfb8aa3b, v58
	v_mul_f32_e32 v59, 0xbfb8aa3b, v59
	v_exp_f32_e32 v56, v56
	v_exp_f32_e32 v57, v57
	v_exp_f32_e32 v58, v58
	v_exp_f32_e32 v59, v59
	v_add_f32_e32 v60, 1.0, v60
	v_add_f32_e32 v61, 1.0, v61
	v_add_f32_e32 v62, 1.0, v62
	v_add_f32_e32 v63, 1.0, v63
	v_rcp_f32_e32 v60, v60
	v_rcp_f32_e32 v61, v61
	v_rcp_f32_e32 v62, v62
	v_rcp_f32_e32 v63, v63
	v_add_f32_e32 v56, 1.0, v56
	v_add_f32_e32 v57, 1.0, v57
	v_add_f32_e32 v58, 1.0, v58
	v_add_f32_e32 v59, 1.0, v59
	v_rcp_f32_e32 v56, v56
	v_rcp_f32_e32 v57, v57
	v_rcp_f32_e32 v58, v58
	v_rcp_f32_e32 v59, v59
	v_lshl_add_u64 v[96:97], v[96:97], 0, v[168:169]
	s_waitcnt vmcnt(7)
	v_lshlrev_b32_e32 v106, 16, v92
	v_and_b32_e32 v107, 0xffff0000, v92
	v_lshlrev_b32_e32 v92, 16, v93
	v_and_b32_e32 v93, 0xffff0000, v93
	s_waitcnt vmcnt(6)
	v_lshlrev_b32_e32 v102, 16, v98
	v_and_b32_e32 v103, 0xffff0000, v98
	v_lshlrev_b32_e32 v98, 16, v99
	v_and_b32_e32 v99, 0xffff0000, v99
	v_pk_add_f32 v[108:109], v[144:145], v[92:93]
	v_pk_add_f32 v[92:93], v[146:147], v[106:107]
	v_lshlrev_b32_e32 v104, 16, v100
	v_pk_fma_f32 v[92:93], v[60:61], v[102:103], v[92:93]
	v_pk_fma_f32 v[60:61], v[62:63], v[98:99], v[108:109]
	v_lshlrev_b32_e32 v62, 16, v94
	v_and_b32_e32 v63, 0xffff0000, v94
	v_lshlrev_b32_e32 v94, 16, v95
	v_and_b32_e32 v95, 0xffff0000, v95
	v_and_b32_e32 v105, 0xffff0000, v100
	v_lshlrev_b32_e32 v100, 16, v101
	v_and_b32_e32 v101, 0xffff0000, v101
	v_pk_add_f32 v[98:99], v[144:145], v[94:95]
	v_pk_add_f32 v[62:63], v[146:147], v[62:63]
	s_nop 0
	v_pk_fma_f32 v[94:95], v[56:57], v[104:105], v[62:63]
	v_pk_fma_f32 v[62:63], v[58:59], v[100:101], v[98:99]
	v_cvt_pk_bf16_f32 v56, v92, v93
	v_cvt_pk_bf16_f32 v57, v60, v61
	v_cvt_pk_bf16_f32 v58, v94, v95
	v_cvt_pk_bf16_f32 v59, v62, v63
	global_store_dwordx4 v[96:97], v[56:59], off
	s_nop 1
	v_mul_f32_e32 v56, v93, v93
	v_mul_f32_e32 v57, v61, v61
	v_fmac_f32_e32 v56, v92, v92
	v_fmac_f32_e32 v57, v60, v60
	v_add_f32_e32 v56, v56, v57
	v_mul_f32_e32 v57, v95, v95
	v_fmac_f32_e32 v57, v94, v94
	v_add_f32_e32 v56, v57, v56
	v_mul_f32_e32 v57, v63, v63
	v_fmac_f32_e32 v57, v62, v62
	v_add_f32_e32 v91, v57, v56
	v_pk_mul_f32 v[54:55], v[54:55], v[90:91] op_sel_hi:[1,0]
	v_pk_mul_f32 v[52:53], v[52:53], v[90:91] op_sel_hi:[1,0]
	v_mul_f32_e32 v54, 0xbfb8aa3b, v54
	v_mul_f32_e32 v52, 0xbfb8aa3b, v52
	v_mul_f32_e32 v53, 0xbfb8aa3b, v53
	v_mul_f32_e32 v55, 0xbfb8aa3b, v55
	v_pk_mul_f32 v[50:51], v[50:51], v[90:91] op_sel_hi:[1,0]
	v_pk_mul_f32 v[48:49], v[48:49], v[90:91] op_sel_hi:[1,0]
	v_exp_f32_e32 v52, v52
	v_exp_f32_e32 v53, v53
	v_exp_f32_e32 v54, v54
	v_exp_f32_e32 v55, v55
	v_mul_f32_e32 v48, 0xbfb8aa3b, v48
	v_mul_f32_e32 v49, 0xbfb8aa3b, v49
	v_mul_f32_e32 v50, 0xbfb8aa3b, v50
	v_mul_f32_e32 v51, 0xbfb8aa3b, v51
	v_exp_f32_e32 v48, v48
	v_exp_f32_e32 v49, v49
	v_exp_f32_e32 v50, v50
	v_exp_f32_e32 v51, v51
	v_add_f32_e32 v52, 1.0, v52
	v_add_f32_e32 v53, 1.0, v53
	v_add_f32_e32 v54, 1.0, v54
	v_add_f32_e32 v55, 1.0, v55
	v_rcp_f32_e32 v52, v52
	v_rcp_f32_e32 v53, v53
	v_rcp_f32_e32 v54, v54
	v_rcp_f32_e32 v55, v55
	v_add_f32_e32 v48, 1.0, v48
	v_add_f32_e32 v49, 1.0, v49
	v_add_f32_e32 v50, 1.0, v50
	v_add_f32_e32 v51, 1.0, v51
	s_waitcnt vmcnt(5)
	v_lshlrev_b32_e32 v56, 16, v84
	v_and_b32_e32 v57, 0xffff0000, v84
	v_lshlrev_b32_e32 v58, 16, v85
	v_and_b32_e32 v59, 0xffff0000, v85
	v_rcp_f32_e32 v48, v48
	v_rcp_f32_e32 v49, v49
	v_rcp_f32_e32 v50, v50
	v_rcp_f32_e32 v51, v51
	v_lshlrev_b32_e32 v84, 16, v80
	v_and_b32_e32 v85, 0xffff0000, v80
	v_lshlrev_b32_e32 v80, 16, v81
	v_and_b32_e32 v81, 0xffff0000, v81
	v_pk_add_f32 v[80:81], v[144:145], v[80:81]
	v_pk_add_f32 v[84:85], v[146:147], v[84:85]
	v_pk_fma_f32 v[54:55], v[54:55], v[58:59], v[80:81]
	v_pk_fma_f32 v[52:53], v[52:53], v[56:57], v[84:85]
	v_lshlrev_b32_e32 v56, 16, v82
	v_and_b32_e32 v57, 0xffff0000, v82
	v_lshlrev_b32_e32 v58, 16, v83
	v_and_b32_e32 v59, 0xffff0000, v83
	v_lshlrev_b32_e32 v60, 16, v86
	v_and_b32_e32 v61, 0xffff0000, v86
	v_lshlrev_b32_e32 v62, 16, v87
	v_and_b32_e32 v63, 0xffff0000, v87
	v_pk_add_f32 v[58:59], v[144:145], v[58:59]
	v_pk_add_f32 v[56:57], v[146:147], v[56:57]
	v_pk_fma_f32 v[58:59], v[50:51], v[62:63], v[58:59]
	v_pk_fma_f32 v[56:57], v[48:49], v[60:61], v[56:57]
	v_cvt_pk_bf16_f32 v48, v52, v53
	v_cvt_pk_bf16_f32 v49, v54, v55
	v_cvt_pk_bf16_f32 v50, v56, v57
	v_cvt_pk_bf16_f32 v51, v58, v59
	global_store_dwordx4 v[96:97], v[48:51], off offset:256
	s_nop 1
	v_mul_f32_e32 v48, v53, v53
	v_mul_f32_e32 v49, v55, v55
	v_fmac_f32_e32 v48, v52, v52
	v_fmac_f32_e32 v49, v54, v54
	v_add_f32_e32 v48, v48, v49
	v_mul_f32_e32 v49, v57, v57
	v_fmac_f32_e32 v49, v56, v56
	v_add_f32_e32 v48, v49, v48
	v_mul_f32_e32 v49, v59, v59
	v_fmac_f32_e32 v49, v58, v58
	v_add_f32_e32 v48, v49, v48
	v_add_f32_e32 v48, v91, v48
	ds_bpermute_b32 v49, v204, v48
	s_waitcnt lgkmcnt(0)
	v_add_f32_e32 v48, v48, v49
	ds_bpermute_b32 v49, v203, v48
	s_and_saveexec_b64 s[12:13], s[42:43]
	s_cbranch_execz .LBB0_587
;     template <int NM> __device__ __forceinline__ void round(const AccT& acc, const Unit& u, int ai, int m0, int wr, int wc, int fr, int fq) const {
;     ...
;             ss += __shfl_xor(ss, 16); ss += __shfl_xor(ss, 32);
;             if (fq == 0) *GP(float, ssp + (size_t)(u.pn * 4 + wc) * TT + row) = ss;
	s_lshl_b32 s20, s25, 2
	s_or_b32 s20, s20, s71
	s_ashr_i32 s21, s20, 31
	s_lshl_b64 s[20:21], s[20:21], 18
	s_add_u32 s20, s65, s20
	s_addc_u32 s21, s70, s21
	s_waitcnt lgkmcnt(0)
	v_add_f32_e32 v50, v48, v49
	v_lshl_add_u64 v[48:49], v[88:89], 2, s[20:21]
	global_store_dword v[48:49], v50, off

;     template <int NM> __device__ __forceinline__ void round(const AccT& acc, const Unit& u, int ai, int m0, int wr, int wc, int fr, int fq) const {
;     ...
;             const int rl = ai * 128 + wr * 64 + (m0 + mm) * 16 + fr;
;             const size_t off = (size_t)(u.pm * 256 + rl) * DM + u.pn * 256 + wc * 32 + 8 * fq;
; #pragma unroll
;             for (int bj = 0; bj < 2; ++bj) {
;                 hv[mm][bj] = *GP(const u32x4, hin + off + bj * 128); lv[mm][bj] = (u32x2){0u, 0u};
;                 if (MODE == 1) pv[mm][bj] = *GP(const u32x4, proj + off + bj * 128);
;             }
;         }
; #pragma unroll
;         for (int mm = 0; mm < NM; ++mm) {
;             const int m = m0 + mm;
;             const int rl = ai * 128 + wr * 64 + m * 16 + fr; const int row = u.pm * 256 + rl;
;             const size_t off = (size_t)row * DM + u.pn * 256 + wc * 32 + 8 * fq;
;             float r = 1.f; if (MODE == 1) r = rs[((u.pm >> 3) & 3) * 256 + rl];
;             float ss = 0.f;
; #pragma unroll
;             for (int bj = 0; bj < 2; ++bj) {
;                 f32x4 d0, d1;
;                 if (MODE == 0) { d0 = acc[ai][bj][m][0] * alpha; d1 = acc[ai][bj][m][1] * alpha; }
;                 else {
;                     const u32x4 p = pv[mm][bj];
;                     const f32x4 a0 = acc[ai][bj][m][0] * r, a1 = acc[ai][bj][m][1] * r;
;                     d0 = (f32x4){fsigmoid(a0[0]) * bflo(p.x), fsigmoid(a0[1]) * bfhi(p.x), fsigmoid(a0[2]) * bflo(p.y), fsigmoid(a0[3]) * bfhi(p.y)};
;                     d1 = (f32x4){fsigmoid(a1[0]) * bflo(p.z), fsigmoid(a1[1]) * bfhi(p.z), fsigmoid(a1[2]) * bflo(p.w), fsigmoid(a1[3]) * bfhi(p.w)};
;                 }
;                 const u32x4 H = hv[mm][bj]; const u32x2 L = lv[mm][bj];
;                 const f32x4 o0 = ((f32x4){bflo(H.x), bfhi(H.x), bflo(H.y), bfhi(H.y)} + lo_unpack4(L.x)) + d0;
;                 const f32x4 o1 = ((f32x4){bflo(H.z), bfhi(H.z), bflo(H.w), bfhi(H.w)} + lo_unpack4(L.y)) + d1;
;                 u32x4 w; w.x = cvt_pk_bf16(o0[0], o0[1]); w.y = cvt_pk_bf16(o0[2], o0[3]); w.z = cvt_pk_bf16(o1[0], o1[1]); w.w = cvt_pk_bf16(o1[2], o1[3]);
;                 u32x2 wl; wl.x = lo_pack4(o0[0] - bflo(w.x), o0[1] - bfhi(w.x), o0[2] - bflo(w.y), o0[3] - bfhi(w.y));
;                 wl.y = lo_pack4(o1[0] - bflo(w.z), o1[1] - bfhi(w.z), o1[2] - bflo(w.w), o1[3] - bfhi(w.w));
.LBB0_589:
	s_or_b64 exec, exec, s[12:13]
	v_or_b32_e32 v32, 32, v88
	s_waitcnt lgkmcnt(0)
	v_ashrrev_i32_e32 v33, 31, v32
	v_lshlrev_b64 v[32:33], 10, v[32:33]
	v_lshl_add_u64 v[32:33], v[32:33], 0, v[158:159]
	v_lshlrev_b64 v[32:33], 1, v[32:33]
	v_lshl_add_u64 v[34:35], s[66:67], 0, v[32:33]
	s_mov_b64 s[26:27], 0x3000
	v_lshl_add_u64 v[32:33], v[176:177], 0, s[26:27]
	global_load_dwordx4 v[56:59], v[34:35], off
	global_load_dwordx4 v[60:63], v[32:33], off
	global_load_dwordx4 v[48:51], v[34:35], off offset:256
	global_load_dwordx4 v[52:55], v[32:33], off offset:1024
	v_or_b32_e32 v32, 48, v88
	v_ashrrev_i32_e32 v33, 31, v32
	v_lshlrev_b64 v[32:33], 10, v[32:33]
	v_lshl_add_u64 v[32:33], v[32:33], 0, v[158:159]
	v_lshlrev_b64 v[32:33], 1, v[32:33]
	v_lshl_add_u64 v[34:35], s[66:67], 0, v[32:33]
	s_mov_b64 s[26:27], 0x3800
	v_lshl_add_u64 v[36:37], v[176:177], 0, s[26:27]
	global_load_dwordx4 v[40:43], v[34:35], off
	global_load_dwordx4 v[44:47], v[36:37], off
	s_nop 0
	global_load_dwordx4 v[32:35], v[34:35], off offset:256
	s_nop 0
	global_load_dwordx4 v[36:39], v[36:37], off offset:1024
	ds_read_b32 v64, v205 offset:640
	v_add_u32_e32 v66, s46, v200
	v_ashrrev_i32_e32 v67, 31, v66
	v_lshlrev_b64 v[66:67], 11, v[66:67]
	s_waitcnt lgkmcnt(0)
	v_pk_mul_f32 v[30:31], v[30:31], v[64:65] op_sel_hi:[1,0]
	v_pk_mul_f32 v[28:29], v[28:29], v[64:65] op_sel_hi:[1,0]
	v_pk_mul_f32 v[68:69], v[26:27], v[64:65] op_sel_hi:[1,0]
	v_pk_mul_f32 v[70:71], v[24:25], v[64:65] op_sel_hi:[1,0]
	v_mul_f32_e32 v24, 0xbfb8aa3b, v28
	v_mul_f32_e32 v25, 0xbfb8aa3b, v29
	v_mul_f32_e32 v28, 0xbfb8aa3b, v30
	v_mul_f32_e32 v29, 0xbfb8aa3b, v31
	v_exp_f32_e32 v24, v24
	v_exp_f32_e32 v25, v25
	v_exp_f32_e32 v28, v28
	v_exp_f32_e32 v29, v29
	v_add_f32_e32 v24, 1.0, v24
	v_add_f32_e32 v25, 1.0, v25
	v_rcp_f32_e32 v24, v24
	v_rcp_f32_e32 v25, v25
	v_add_f32_e32 v28, 1.0, v28
	v_add_f32_e32 v29, 1.0, v29
	v_rcp_f32_e32 v28, v28
	v_rcp_f32_e32 v29, v29
	v_pk_mul_f32 v[22:23], v[22:23], v[64:65] op_sel_hi:[1,0]
	v_pk_mul_f32 v[20:21], v[20:21], v[64:65] op_sel_hi:[1,0]
	v_mul_f32_e32 v22, 0xbfb8aa3b, v22
	v_mul_f32_e32 v20, 0xbfb8aa3b, v20
	v_mul_f32_e32 v21, 0xbfb8aa3b, v21
	v_mul_f32_e32 v23, 0xbfb8aa3b, v23
	v_pk_mul_f32 v[18:19], v[18:19], v[64:65] op_sel_hi:[1,0]
	v_pk_mul_f32 v[16:17], v[16:17], v[64:65] op_sel_hi:[1,0]
	v_exp_f32_e32 v20, v20
	v_exp_f32_e32 v21, v21
	v_exp_f32_e32 v22, v22
	v_exp_f32_e32 v23, v23
	v_mul_f32_e32 v16, 0xbfb8aa3b, v16
	v_mul_f32_e32 v17, 0xbfb8aa3b, v17
	v_mul_f32_e32 v18, 0xbfb8aa3b, v18
	v_mul_f32_e32 v19, 0xbfb8aa3b, v19
	v_exp_f32_e32 v16, v16
	v_exp_f32_e32 v17, v17
	v_exp_f32_e32 v18, v18
	v_exp_f32_e32 v19, v19
	v_add_f32_e32 v20, 1.0, v20
	v_add_f32_e32 v21, 1.0, v21
	v_add_f32_e32 v22, 1.0, v22
	v_add_f32_e32 v23, 1.0, v23
	v_rcp_f32_e32 v20, v20
	v_rcp_f32_e32 v21, v21
	v_rcp_f32_e32 v22, v22
	v_rcp_f32_e32 v23, v23
	v_add_f32_e32 v16, 1.0, v16
	v_add_f32_e32 v17, 1.0, v17
	v_add_f32_e32 v18, 1.0, v18
	v_add_f32_e32 v19, 1.0, v19
	v_rcp_f32_e32 v16, v16
	v_rcp_f32_e32 v17, v17
	v_rcp_f32_e32 v18, v18
	v_rcp_f32_e32 v19, v19
	s_waitcnt vmcnt(7)
	v_lshlrev_b32_e32 v72, 16, v56
	s_waitcnt vmcnt(6)
	v_lshlrev_b32_e32 v26, 16, v60
	v_and_b32_e32 v27, 0xffff0000, v60
	v_lshlrev_b32_e32 v30, 16, v61
	v_and_b32_e32 v31, 0xffff0000, v61
	v_mul_f32_e32 v60, 0xbfb8aa3b, v70
	v_mul_f32_e32 v61, 0xbfb8aa3b, v71
	v_lshlrev_b32_e32 v70, 16, v62
	v_and_b32_e32 v71, 0xffff0000, v62
	v_mul_f32_e32 v62, 0xbfb8aa3b, v68
	v_exp_f32_e32 v62, v62
	v_exp_f32_e32 v60, v60
	v_exp_f32_e32 v61, v61
	v_and_b32_e32 v73, 0xffff0000, v56
	v_add_f32_e32 v62, 1.0, v62
	v_rcp_f32_e32 v68, v62
	v_mul_f32_e32 v62, 0xbfb8aa3b, v69
	v_exp_f32_e32 v62, v62
	v_add_f32_e32 v60, 1.0, v60
	v_add_f32_e32 v61, 1.0, v61
	v_rcp_f32_e32 v60, v60
	v_add_f32_e32 v62, 1.0, v62
	v_rcp_f32_e32 v61, v61
	v_rcp_f32_e32 v69, v62
	v_pk_add_f32 v[72:73], v[146:147], v[72:73]
	v_lshlrev_b32_e32 v56, 16, v57
	v_and_b32_e32 v57, 0xffff0000, v57
	v_pk_fma_f32 v[72:73], v[24:25], v[26:27], v[72:73]
	v_lshlrev_b32_e32 v24, 16, v58
	v_and_b32_e32 v25, 0xffff0000, v58
	v_lshlrev_b32_e32 v26, 16, v59
	v_and_b32_e32 v27, 0xffff0000, v59
	v_lshl_add_u64 v[58:59], s[14:15], 0, v[66:67]
	v_lshlrev_b32_e32 v62, 16, v63
	v_and_b32_e32 v63, 0xffff0000, v63
	v_pk_add_f32 v[56:57], v[144:145], v[56:57]
	v_pk_add_f32 v[26:27], v[144:145], v[26:27]
	v_pk_add_f32 v[24:25], v[146:147], v[24:25]
	v_lshl_add_u64 v[58:59], s[16:17], 1, v[58:59]
	v_pk_fma_f32 v[28:29], v[28:29], v[30:31], v[56:57]
	v_pk_fma_f32 v[30:31], v[60:61], v[70:71], v[24:25]
	v_pk_fma_f32 v[56:57], v[68:69], v[62:63], v[26:27]
	v_lshl_add_u64 v[58:59], v[58:59], 0, s[62:63]
	v_cvt_pk_bf16_f32 v24, v72, v73
	v_cvt_pk_bf16_f32 v25, v28, v29
	v_cvt_pk_bf16_f32 v26, v30, v31
	v_cvt_pk_bf16_f32 v27, v56, v57
	v_lshl_add_u64 v[58:59], v[58:59], 0, v[168:169]
	global_store_dwordx4 v[58:59], v[24:27], off
	s_nop 1
	v_mul_f32_e32 v24, v73, v73
	v_mul_f32_e32 v25, v29, v29
	v_fmac_f32_e32 v24, v72, v72
	v_fmac_f32_e32 v25, v28, v28
	v_add_f32_e32 v24, v24, v25
	v_mul_f32_e32 v25, v31, v31
	v_fmac_f32_e32 v25, v30, v30
	v_add_f32_e32 v24, v25, v24
	v_mul_f32_e32 v25, v57, v57
	v_fmac_f32_e32 v25, v56, v56
	v_add_f32_e32 v56, v25, v24
	s_waitcnt vmcnt(5)
	v_lshlrev_b32_e32 v24, 16, v52
	v_and_b32_e32 v25, 0xffff0000, v52
	v_lshlrev_b32_e32 v26, 16, v53
	v_and_b32_e32 v27, 0xffff0000, v53
	v_lshlrev_b32_e32 v52, 16, v48
	v_and_b32_e32 v53, 0xffff0000, v48
	v_lshlrev_b32_e32 v48, 16, v49
	v_and_b32_e32 v49, 0xffff0000, v49
	v_pk_add_f32 v[48:49], v[144:145], v[48:49]
	v_pk_add_f32 v[52:53], v[146:147], v[52:53]
	v_pk_fma_f32 v[22:23], v[22:23], v[26:27], v[48:49]
	v_pk_fma_f32 v[20:21], v[20:21], v[24:25], v[52:53]
	v_lshlrev_b32_e32 v24, 16, v50
	v_and_b32_e32 v25, 0xffff0000, v50
	v_lshlrev_b32_e32 v26, 16, v51
	v_and_b32_e32 v27, 0xffff0000, v51
	v_lshlrev_b32_e32 v28, 16, v54
	v_and_b32_e32 v29, 0xffff0000, v54
	v_lshlrev_b32_e32 v30, 16, v55
	v_and_b32_e32 v31, 0xffff0000, v55
	v_pk_add_f32 v[26:27], v[144:145], v[26:27]
	v_pk_add_f32 v[24:25], v[146:147], v[24:25]
	v_pk_fma_f32 v[26:27], v[18:19], v[30:31], v[26:27]
	v_pk_fma_f32 v[24:25], v[16:17], v[28:29], v[24:25]
	v_cvt_pk_bf16_f32 v16, v20, v21
	v_cvt_pk_bf16_f32 v17, v22, v23
	v_cvt_pk_bf16_f32 v18, v24, v25
	v_cvt_pk_bf16_f32 v19, v26, v27
	global_store_dwordx4 v[58:59], v[16:19], off offset:256
	s_nop 1
	v_mul_f32_e32 v16, v21, v21
	v_mul_f32_e32 v17, v23, v23
	v_fmac_f32_e32 v16, v20, v20
	v_fmac_f32_e32 v17, v22, v22
	v_add_f32_e32 v16, v16, v17
	v_mul_f32_e32 v17, v25, v25
	v_fmac_f32_e32 v17, v24, v24
	v_add_f32_e32 v16, v17, v16
	v_mul_f32_e32 v17, v27, v27
	v_fmac_f32_e32 v17, v26, v26
	v_add_f32_e32 v16, v17, v16
	v_add_f32_e32 v16, v56, v16
	ds_bpermute_b32 v17, v204, v16
	s_waitcnt lgkmcnt(0)
	v_add_f32_e32 v16, v16, v17
	ds_bpermute_b32 v17, v203, v16
	s_and_saveexec_b64 s[12:13], s[42:43]
	s_cbranch_execz .LBB0_591
;     template <int NM> __device__ __forceinline__ void round(const AccT& acc, const Unit& u, int ai, int m0, int wr, int wc, int fr, int fq) const {
;     ...
;             ss += __shfl_xor(ss, 16); ss += __shfl_xor(ss, 32);
;             if (fq == 0) *GP(float, ssp + (size_t)(u.pn * 4 + wc) * TT + row) = ss;
	s_lshl_b32 s20, s25, 2
	s_or_b32 s20, s20, s71
	s_ashr_i32 s21, s20, 31
	s_lshl_b64 s[20:21], s[20:21], 18
	s_add_u32 s20, s65, s20
	s_addc_u32 s21, s70, s21
	s_ashr_i32 s47, s46, 31
	s_waitcnt lgkmcnt(0)
	v_add_f32_e32 v18, v16, v17
	v_lshl_add_u64 v[16:17], s[46:47], 0, v[154:155]
	v_lshl_add_u64 v[16:17], v[16:17], 2, s[20:21]
	global_store_dword v[16:17], v18, off offset:512
